# stackA + SWA band loop: K-fragment reads batched, V transpose-reads hoisted above softmax (loop chunks)
# speedup vs baseline: 1.0267x; 1.0127x over previous
; #define LAS __attribute__((address_space(3)))
; template <int HD, int DV, int HW, int MODE> ...
;     ...
; #pragma unroll
;             for (int i = 0; i < 16; ++i) S[i] = __builtin_amdgcn_exp2f(S[i] - m);
;             l += sum16(S);
;             const bf16x8 P0 = pack8(S, 0), P1 = pack8(S, 8);
; #pragma unroll
;             for (int t = 0; t < NTV; ++t) {
;                 const LAS unsigned char* vb = vread + (32 * u) * RSV + 64 * t;
;                 const bf16x8 v0 = tr_pair(vb, vb + 4 * RSV), v1 = tr_pair(vb + 16 * RSV, vb + 20 * RSV);
;                 O[t] = __builtin_amdgcn_mfma_f32_32x32x16_bf16(v0, P0, O[t], 0, 0, 0);
;                 O[t] = __builtin_amdgcn_mfma_f32_32x32x16_bf16(v1, P1, O[t], 0, 0, 0);
;             }
.LBB0_169:
	v_sub_f32_e32 v3, v48, v115
	v_exp_f32_e32 v8, v3
	v_sub_f32_e32 v3, v49, v115
	v_exp_f32_e32 v10, v3
	v_sub_f32_e32 v3, v50, v115
	v_exp_f32_e32 v12, v3
	v_sub_f32_e32 v3, v51, v115
	v_exp_f32_e32 v14, v3
	v_sub_f32_e32 v3, v52, v115
	v_exp_f32_e32 v48, v3
	v_sub_f32_e32 v3, v53, v115
	v_exp_f32_e32 v50, v3
	v_sub_f32_e32 v3, v54, v115
	v_exp_f32_e32 v52, v3
	v_sub_f32_e32 v3, v55, v115
	v_exp_f32_e32 v54, v3
	v_sub_f32_e32 v3, v56, v115
	v_exp_f32_e32 v9, v3
	v_sub_f32_e32 v3, v57, v115
	v_exp_f32_e32 v11, v3
	v_sub_f32_e32 v3, v58, v115
	v_exp_f32_e32 v13, v3
	v_sub_f32_e32 v3, v59, v115
	v_exp_f32_e32 v15, v3
	v_sub_f32_e32 v3, v60, v115
	v_exp_f32_e32 v49, v3
	v_sub_f32_e32 v3, v61, v115
	v_exp_f32_e32 v51, v3
	v_sub_f32_e32 v3, v62, v115
	v_exp_f32_e32 v53, v3
	v_sub_f32_e32 v3, v63, v115
	v_exp_f32_e32 v55, v3
	v_pk_add_f32 v[4:5], v[8:9], v[10:11]
	v_pk_add_f32 v[6:7], v[12:13], v[14:15]
	v_pk_add_f32 v[56:57], v[52:53], v[54:55]
	v_pk_add_f32 v[4:5], v[4:5], v[6:7]
	v_pk_add_f32 v[6:7], v[48:49], v[50:51]
	s_nop 0
	v_pk_add_f32 v[6:7], v[6:7], v[56:57]
	s_nop 0
	v_pk_add_f32 v[4:5], v[4:5], v[6:7]
	v_cvt_pk_bf16_f32 v7, v52, v54
	v_add_u32_e32 v52, v103, v105
	v_add_f32_e32 v3, v4, v5
	v_cvt_pk_bf16_f32 v4, v8, v10
	v_cvt_pk_bf16_f32 v5, v12, v14
	v_cvt_pk_bf16_f32 v6, v48, v50
	v_cvt_pk_bf16_f32 v8, v9, v11
	v_cvt_pk_bf16_f32 v9, v13, v15
	v_cvt_pk_bf16_f32 v10, v49, v51
	s_waitcnt lgkmcnt(6)
	v_mfma_f32_32x32x16_bf16 v[32:47], v[138:141], v[4:7], v[32:47]
	v_cvt_pk_bf16_f32 v11, v53, v55
	v_add_f32_e32 v101, v101, v3
	s_waitcnt lgkmcnt(4)
	v_mfma_f32_32x32x16_bf16 v[32:47], v[142:145], v[8:11], v[32:47]
	s_waitcnt lgkmcnt(2)
	v_mfma_f32_32x32x16_bf16 v[16:31], v[146:149], v[4:7], v[16:31]
	s_waitcnt lgkmcnt(0)
	v_mfma_f32_32x32x16_bf16 v[16:31], v[150:153], v[8:11], v[16:31]

; #define LAS __attribute__((address_space(3)))
; __device__ __forceinline__ float xmax32(float v) { const auto r = __builtin_amdgcn_permlane32_swap(__float_as_uint(v), __float_as_uint(v), false, false); return __builtin_fmaxf(__uint_as_float(r[0]), __uint_as_float(r[1])); }
; template <int HD, int DV, int HW, int MODE> ...
;     ...
;             const int js = jc + 32 * u;
;             if (js + 31 < iw - HW || js > iw + 31 + HW || js + 31 < 0 || js >= L) continue;
;             f32x16 S;
; #pragma unroll
;             for (int i = 0; i < 16; ++i) S[i] = 0.f;
; #pragma unroll
;             for (int ks = 0; ks < KS; ++ks) { const bf16x8 kf = *(const LAS bf16x8*)(kread + (32 * u) * RSK + 32 * ks); S = __builtin_amdgcn_mfma_f32_32x32x16_bf16(kf, qf[ks], S, 0, 0, 0); }
;             const bool full = (js >= iw + 31 - HW) && (js + 31 <= iw + HW) && js >= 0 && js + 31 < L;
;             if (!full) {
;                 const int qi = iw + ql;
; #pragma unroll
;                 for (int i = 0; i < 16; ++i) { const int j = js + (i & 7) + 8 * hh + 16 * (i >> 3); const int d = qi - j; const bool ok = (d <= HW) && (d >= -HW) && (j >= 0) && (j < L); S[i] = ok ? S[i] : -INFINITY; }
;             }
;             float mt = xmax32(max16(S));
;             if (__any(mt > m + 8.0f)) {
;                 const float mn = fmaxf(m, mt), a = __builtin_amdgcn_exp2f(m - mn); l *= a; m = mn;
; #pragma unroll
;                 for (int t = 0; t < NTV; ++t) O[t] = O[t] * a;
;             }
; #pragma unroll
;             for (int i = 0; i < 16; ++i) S[i] = __builtin_amdgcn_exp2f(S[i] - m);
;             l += sum16(S);
;             const bf16x8 P0 = pack8(S, 0), P1 = pack8(S, 8);
; #pragma unroll
;             for (int t = 0; t < NTV; ++t) {
;                 const LAS unsigned char* vb = vread + (32 * u) * RSV + 64 * t;
;                 const bf16x8 v0 = tr_pair(vb, vb + 4 * RSV), v1 = tr_pair(vb + 16 * RSV, vb + 20 * RSV);
.LBB0_179:
	s_or_b64 exec, exec, s[42:43]
	s_add_i32 s25, s4, s5
	s_add_i32 s23, s25, 0xffffff80
	s_add_i32 s2, s25, 0xffffff9f
	s_cmp_lt_i32 s2, s53
	s_cselect_b64 s[10:11], -1, 0
	s_cmp_gt_i32 s23, s52
	s_cselect_b64 s[28:29], -1, 0
	s_or_b64 s[10:11], s[10:11], s[28:29]
	s_cmpk_gt_u32 s2, 0x201e
	s_cselect_b64 s[28:29], -1, 0
	s_or_b64 s[10:11], s[28:29], s[10:11]
	s_and_b64 vcc, exec, s[10:11]
	s_cbranch_vccnz .LBB0_187
	v_add_u32_e32 v3, v117, v102
	ds_read_b128 v[4:7], v3
	ds_read_b128 v[126:129], v3 offset:32
	ds_read_b128 v[130:133], v3 offset:64
	ds_read_b128 v[134:137], v3 offset:96
	s_cmp_lt_i32 s23, s49
	s_cselect_b64 s[40:41], -1, 0
	s_and_b64 vcc, exec, s[40:41]
	s_waitcnt lgkmcnt(3)
	v_mfma_f32_32x32x16_bf16 v[48:63], v[4:7], v[76:79], 0
	s_waitcnt lgkmcnt(2)
	v_mfma_f32_32x32x16_bf16 v[48:63], v[126:129], v[72:75], v[48:63]
	s_waitcnt lgkmcnt(1)
	v_mfma_f32_32x32x16_bf16 v[48:63], v[130:133], v[68:71], v[48:63]
	s_waitcnt lgkmcnt(0)
	v_mfma_f32_32x32x16_bf16 v[48:63], v[134:137], v[64:67], v[48:63]
	v_add_u32_e32 v154, v103, v105
	ds_read_b64_tr_b16 v[138:139], v154 offset:18432
	ds_read_b64_tr_b16 v[140:141], v154 offset:19200
	ds_read_b64_tr_b16 v[142:143], v154 offset:21504
	ds_read_b64_tr_b16 v[144:145], v154 offset:22272
	ds_read_b64_tr_b16 v[146:147], v154 offset:18496
	ds_read_b64_tr_b16 v[148:149], v154 offset:19264
	ds_read_b64_tr_b16 v[150:151], v154 offset:21568
	ds_read_b64_tr_b16 v[152:153], v154 offset:22336
	s_cbranch_vccnz .LBB0_182
	s_cmp_gt_i32 s23, s47
	s_cselect_b64 s[10:11], -1, 0
	s_cmpk_gt_u32 s23, 0x1fe0
	s_cselect_b64 s[28:29], -1, 0
	s_or_b64 s[40:41], s[10:11], s[28:29]

; #define LAS __attribute__((address_space(3)))
; __device__ __forceinline__ float xmax32(float v) { const auto r = __builtin_amdgcn_permlane32_swap(__float_as_uint(v), __float_as_uint(v), false, false); return __builtin_fmaxf(__uint_as_float(r[0]), __uint_as_float(r[1])); }
; template <int HD, int DV, int HW, int MODE> ...
;     ...
;             const int js = jc + 32 * u;
;             if (js + 31 < iw - HW || js > iw + 31 + HW || js + 31 < 0 || js >= L) continue;
;             f32x16 S;
; #pragma unroll
;             for (int i = 0; i < 16; ++i) S[i] = 0.f;
; #pragma unroll
;             for (int ks = 0; ks < KS; ++ks) { const bf16x8 kf = *(const LAS bf16x8*)(kread + (32 * u) * RSK + 32 * ks); S = __builtin_amdgcn_mfma_f32_32x32x16_bf16(kf, qf[ks], S, 0, 0, 0); }
;             const bool full = (js >= iw + 31 - HW) && (js + 31 <= iw + HW) && js >= 0 && js + 31 < L;
;             if (!full) {
;                 const int qi = iw + ql;
; #pragma unroll
;                 for (int i = 0; i < 16; ++i) { const int j = js + (i & 7) + 8 * hh + 16 * (i >> 3); const int d = qi - j; const bool ok = (d <= HW) && (d >= -HW) && (j >= 0) && (j < L); S[i] = ok ? S[i] : -INFINITY; }
;             }
;             float mt = xmax32(max16(S));
;             if (__any(mt > m + 8.0f)) {
;                 const float mn = fmaxf(m, mt), a = __builtin_amdgcn_exp2f(m - mn); l *= a; m = mn;
; #pragma unroll
;                 for (int t = 0; t < NTV; ++t) O[t] = O[t] * a;
;             }
; #pragma unroll
;             for (int i = 0; i < 16; ++i) S[i] = __builtin_amdgcn_exp2f(S[i] - m);
;             l += sum16(S);
;             const bf16x8 P0 = pack8(S, 0), P1 = pack8(S, 8);
; #pragma unroll
;             for (int t = 0; t < NTV; ++t) {
;                 const LAS unsigned char* vb = vread + (32 * u) * RSV + 64 * t;
;                 const bf16x8 v0 = tr_pair(vb, vb + 4 * RSV), v1 = tr_pair(vb + 16 * RSV, vb + 20 * RSV);
.LBB0_187:
	s_add_i32 s28, s25, 0xffffffa0
	s_add_i32 s2, s25, 0xffffffbf
	s_cmp_lt_i32 s2, s53
	s_cselect_b64 s[10:11], -1, 0
	s_cmp_gt_i32 s28, s52
	s_cselect_b64 s[40:41], -1, 0
	s_or_b64 s[10:11], s[10:11], s[40:41]
	s_cmpk_gt_u32 s2, 0x201e
	s_cselect_b64 s[40:41], -1, 0
	s_or_b64 s[10:11], s[40:41], s[10:11]
	s_and_b64 vcc, exec, s[10:11]
	s_cbranch_vccnz .LBB0_195
	v_add_u32_e32 v3, v117, v102
	ds_read_b128 v[4:7], v3 offset:4608
	ds_read_b128 v[126:129], v3 offset:4640
	ds_read_b128 v[130:133], v3 offset:4672
	ds_read_b128 v[134:137], v3 offset:4704
	s_cmp_lt_i32 s28, s49
	s_cselect_b64 s[40:41], -1, 0
	s_and_b64 vcc, exec, s[40:41]
	s_waitcnt lgkmcnt(3)
	v_mfma_f32_32x32x16_bf16 v[48:63], v[4:7], v[76:79], 0
	s_waitcnt lgkmcnt(2)
	v_mfma_f32_32x32x16_bf16 v[48:63], v[126:129], v[72:75], v[48:63]
	s_waitcnt lgkmcnt(1)
	v_mfma_f32_32x32x16_bf16 v[48:63], v[130:133], v[68:71], v[48:63]
	s_waitcnt lgkmcnt(0)
	v_mfma_f32_32x32x16_bf16 v[48:63], v[134:137], v[64:67], v[48:63]
	v_add_u32_e32 v154, v103, v105
	ds_read_b64_tr_b16 v[138:139], v154 offset:24576
	ds_read_b64_tr_b16 v[140:141], v154 offset:25344
	ds_read_b64_tr_b16 v[142:143], v154 offset:27648
	ds_read_b64_tr_b16 v[144:145], v154 offset:28416
	ds_read_b64_tr_b16 v[146:147], v154 offset:24640
	ds_read_b64_tr_b16 v[148:149], v154 offset:25408
	ds_read_b64_tr_b16 v[150:151], v154 offset:27712
	ds_read_b64_tr_b16 v[152:153], v154 offset:28480
	s_cbranch_vccnz .LBB0_190
	s_cmp_gt_i32 s28, s47
	s_cselect_b64 s[10:11], -1, 0
	s_cmpk_gt_u32 s28, 0x1fe0
	s_cselect_b64 s[28:29], -1, 0
	s_or_b64 s[40:41], s[10:11], s[28:29]

; #define LAS __attribute__((address_space(3)))
; __device__ __forceinline__ float xmax32(float v) { const auto r = __builtin_amdgcn_permlane32_swap(__float_as_uint(v), __float_as_uint(v), false, false); return __builtin_fmaxf(__uint_as_float(r[0]), __uint_as_float(r[1])); }
; template <int HD, int DV, int HW, int MODE> ...
;     ...
;             const int js = jc + 32 * u;
;             if (js + 31 < iw - HW || js > iw + 31 + HW || js + 31 < 0 || js >= L) continue;
;             f32x16 S;
; #pragma unroll
;             for (int i = 0; i < 16; ++i) S[i] = 0.f;
; #pragma unroll
;             for (int ks = 0; ks < KS; ++ks) { const bf16x8 kf = *(const LAS bf16x8*)(kread + (32 * u) * RSK + 32 * ks); S = __builtin_amdgcn_mfma_f32_32x32x16_bf16(kf, qf[ks], S, 0, 0, 0); }
;             const bool full = (js >= iw + 31 - HW) && (js + 31 <= iw + HW) && js >= 0 && js + 31 < L;
;             if (!full) {
;                 const int qi = iw + ql;
; #pragma unroll
;                 for (int i = 0; i < 16; ++i) { const int j = js + (i & 7) + 8 * hh + 16 * (i >> 3); const int d = qi - j; const bool ok = (d <= HW) && (d >= -HW) && (j >= 0) && (j < L); S[i] = ok ? S[i] : -INFINITY; }
;             }
;             float mt = xmax32(max16(S));
;             if (__any(mt > m + 8.0f)) {
;                 const float mn = fmaxf(m, mt), a = __builtin_amdgcn_exp2f(m - mn); l *= a; m = mn;
; #pragma unroll
;                 for (int t = 0; t < NTV; ++t) O[t] = O[t] * a;
;             }
; #pragma unroll
;             for (int i = 0; i < 16; ++i) S[i] = __builtin_amdgcn_exp2f(S[i] - m);
;             l += sum16(S);
;             const bf16x8 P0 = pack8(S, 0), P1 = pack8(S, 8);
; #pragma unroll
;             for (int t = 0; t < NTV; ++t) {
;                 const LAS unsigned char* vb = vread + (32 * u) * RSV + 64 * t;
;                 const bf16x8 v0 = tr_pair(vb, vb + 4 * RSV), v1 = tr_pair(vb + 16 * RSV, vb + 20 * RSV);
.LBB0_195:
	s_sub_i32 s28, s25, 64
	s_sub_i32 s2, s25, 33
	s_cmp_lt_i32 s2, s53
	s_cselect_b64 s[10:11], -1, 0
	s_cmp_gt_i32 s28, s52
	s_cselect_b64 s[40:41], -1, 0
	s_or_b64 s[10:11], s[10:11], s[40:41]
	s_cmpk_gt_u32 s2, 0x201e
	s_cselect_b64 s[40:41], -1, 0
	s_or_b64 s[10:11], s[40:41], s[10:11]
	s_and_b64 vcc, exec, s[10:11]
	s_cbranch_vccnz .LBB0_203
	v_add_u32_e32 v3, v117, v102
	ds_read_b128 v[4:7], v3 offset:9216
	ds_read_b128 v[126:129], v3 offset:9248
	ds_read_b128 v[130:133], v3 offset:9280
	ds_read_b128 v[134:137], v3 offset:9312
	s_cmp_lt_i32 s28, s49
	s_cselect_b64 s[40:41], -1, 0
	s_and_b64 vcc, exec, s[40:41]
	s_waitcnt lgkmcnt(3)
	v_mfma_f32_32x32x16_bf16 v[48:63], v[4:7], v[76:79], 0
	s_waitcnt lgkmcnt(2)
	v_mfma_f32_32x32x16_bf16 v[48:63], v[126:129], v[72:75], v[48:63]
	s_waitcnt lgkmcnt(1)
	v_mfma_f32_32x32x16_bf16 v[48:63], v[130:133], v[68:71], v[48:63]
	s_waitcnt lgkmcnt(0)
	v_mfma_f32_32x32x16_bf16 v[48:63], v[134:137], v[64:67], v[48:63]
	v_add_u32_e32 v154, v103, v105
	ds_read_b64_tr_b16 v[138:139], v154 offset:30720
	ds_read_b64_tr_b16 v[140:141], v154 offset:31488
	ds_read_b64_tr_b16 v[142:143], v154 offset:33792
	ds_read_b64_tr_b16 v[144:145], v154 offset:34560
	ds_read_b64_tr_b16 v[146:147], v154 offset:30784
	ds_read_b64_tr_b16 v[148:149], v154 offset:31552
	ds_read_b64_tr_b16 v[150:151], v154 offset:33856
	ds_read_b64_tr_b16 v[152:153], v154 offset:34624
	s_cbranch_vccnz .LBB0_198
	s_cmp_gt_i32 s28, s47
	s_cselect_b64 s[10:11], -1, 0
	s_cmpk_gt_u32 s28, 0x1fe0
	s_cselect_b64 s[28:29], -1, 0
	s_or_b64 s[40:41], s[10:11], s[28:29]

; #define LAS __attribute__((address_space(3)))
; __device__ __forceinline__ float xmax32(float v) { const auto r = __builtin_amdgcn_permlane32_swap(__float_as_uint(v), __float_as_uint(v), false, false); return __builtin_fmaxf(__uint_as_float(r[0]), __uint_as_float(r[1])); }
; template <int HD, int DV, int HW, int MODE> ...
;     ...
;             const int js = jc + 32 * u;
;             if (js + 31 < iw - HW || js > iw + 31 + HW || js + 31 < 0 || js >= L) continue;
;             f32x16 S;
; #pragma unroll
;             for (int i = 0; i < 16; ++i) S[i] = 0.f;
; #pragma unroll
;             for (int ks = 0; ks < KS; ++ks) { const bf16x8 kf = *(const LAS bf16x8*)(kread + (32 * u) * RSK + 32 * ks); S = __builtin_amdgcn_mfma_f32_32x32x16_bf16(kf, qf[ks], S, 0, 0, 0); }
;             const bool full = (js >= iw + 31 - HW) && (js + 31 <= iw + HW) && js >= 0 && js + 31 < L;
;             if (!full) {
;                 const int qi = iw + ql;
; #pragma unroll
;                 for (int i = 0; i < 16; ++i) { const int j = js + (i & 7) + 8 * hh + 16 * (i >> 3); const int d = qi - j; const bool ok = (d <= HW) && (d >= -HW) && (j >= 0) && (j < L); S[i] = ok ? S[i] : -INFINITY; }
;             }
;             float mt = xmax32(max16(S));
;             if (__any(mt > m + 8.0f)) {
;                 const float mn = fmaxf(m, mt), a = __builtin_amdgcn_exp2f(m - mn); l *= a; m = mn;
; #pragma unroll
;                 for (int t = 0; t < NTV; ++t) O[t] = O[t] * a;
;             }
; #pragma unroll
;             for (int i = 0; i < 16; ++i) S[i] = __builtin_amdgcn_exp2f(S[i] - m);
;             l += sum16(S);
;             const bf16x8 P0 = pack8(S, 0), P1 = pack8(S, 8);
; #pragma unroll
;             for (int t = 0; t < NTV; ++t) {
;                 const LAS unsigned char* vb = vread + (32 * u) * RSV + 64 * t;
;                 const bf16x8 v0 = tr_pair(vb, vb + 4 * RSV), v1 = tr_pair(vb + 16 * RSV, vb + 20 * RSV);
.LBB0_203:
	s_sub_i32 s28, s25, 32
	s_add_i32 s25, s25, -1
	s_cmp_lt_i32 s25, s53
	s_cselect_b64 s[10:11], -1, 0
	s_cmp_gt_i32 s28, s52
	s_cselect_b64 s[40:41], -1, 0
	s_or_b64 s[10:11], s[10:11], s[40:41]
	s_cmpk_gt_u32 s25, 0x201e
	s_cselect_b64 s[40:41], -1, 0
	s_or_b64 s[10:11], s[40:41], s[10:11]
	s_and_b64 vcc, exec, s[10:11]
	s_cbranch_vccnz .LBB0_170
	v_add_u32_e32 v3, v117, v102
	ds_read_b128 v[4:7], v3 offset:13824
	ds_read_b128 v[126:129], v3 offset:13856
	ds_read_b128 v[130:133], v3 offset:13888
	ds_read_b128 v[134:137], v3 offset:13920
	s_cmp_lt_i32 s28, s49
	s_cselect_b64 s[40:41], -1, 0
	s_and_b64 vcc, exec, s[40:41]
	s_waitcnt lgkmcnt(3)
	v_mfma_f32_32x32x16_bf16 v[48:63], v[4:7], v[76:79], 0
	s_waitcnt lgkmcnt(2)
	v_mfma_f32_32x32x16_bf16 v[48:63], v[126:129], v[72:75], v[48:63]
	s_waitcnt lgkmcnt(1)
	v_mfma_f32_32x32x16_bf16 v[48:63], v[130:133], v[68:71], v[48:63]
	s_waitcnt lgkmcnt(0)
	v_mfma_f32_32x32x16_bf16 v[48:63], v[134:137], v[64:67], v[48:63]
	v_add_u32_e32 v154, v103, v105
	ds_read_b64_tr_b16 v[138:139], v154 offset:36864
	ds_read_b64_tr_b16 v[140:141], v154 offset:37632
	ds_read_b64_tr_b16 v[142:143], v154 offset:39936
	ds_read_b64_tr_b16 v[144:145], v154 offset:40704
	ds_read_b64_tr_b16 v[146:147], v154 offset:36928
	ds_read_b64_tr_b16 v[148:149], v154 offset:37696
	ds_read_b64_tr_b16 v[150:151], v154 offset:40000
	ds_read_b64_tr_b16 v[152:153], v154 offset:40768
	s_cbranch_vccnz .LBB0_206
	s_cmp_gt_i32 s28, s47
	s_cselect_b64 s[10:11], -1, 0
	s_cmpk_gt_u32 s28, 0x1fe0
	s_cselect_b64 s[28:29], -1, 0
	s_or_b64 s[40:41], s[10:11], s[28:29]
